# leading wave group: next-tile staging addresses from SGPR bases computed once per unit (2 VALU per tile instead of 6-7, no vcc carry chains)
# speedup vs baseline: 1.0065x; 1.0065x over previous
; __device__ __forceinline__ int v_st(int k, int c) { const int kk = (k & ~0xC) | ((k & 4) << 1) | ((k & 8) >> 1); return ((kk >> 3) * 4 + (c >> 5)) * 512 + ((kk & 7) * 32 + (c & 31)) * 2; }
; __device__ __forceinline__ int v_rd_base(int lane) { return ((lane & 3) << 3) | (((lane >> 2) & 3) << 6) | (((lane >> 4) & 1) << 5) | (((lane >> 5) & 1) << 8); }
; #define SLOAD(t) do { const long r0_ = TROW(t); const bf16_t* vp_ = Vh + r0_ * LDV + vgo0; const bf16_t* kp_ = Kh + r0_ * LDKK + kgo0; \
;     vs0 = *reinterpret_cast<const bf16x8*>(vp_); vs1 = *reinterpret_cast<const bf16x8*>(vp_ + 64); \
;     ks0 = *reinterpret_cast<const bf16x8*>(kp_); ks1 = *reinterpret_cast<const bf16x8*>(kp_ + 64); ks2 = *reinterpret_cast<const bf16x8*>(kp_ + 128); } while (0)
; #define SWRITE(b) do { *(bf16x8*)(V_lds + (b) * SHM_V + vst0) = vs0; *(bf16x8*)(V_lds + (b) * SHM_V + vst0 + 1024) = vs1; \
;     *(bf16x8*)(K_lds + (b) * SHM_K + klo0) = ks0; *(bf16x8*)(K_lds + (b) * SHM_K + klo0 + 128) = ks1; *(bf16x8*)(K_lds + (b) * SHM_K + klo0 + 256) = ks2; } while (0)
; #define SWAIT() asm volatile("s_waitcnt vmcnt(0)" ::: "memory")
; #define SLOAD(t) do { const long r0_ = TROW(t); const bf16_t* vp_ = Vh + r0_ * LDV + vgo0; const bf16_t* kp_ = Kh + r0_ * LDKK + kgo0; \
;     vs0 = *reinterpret_cast<const bf16x8*>(vp_); vs1 = *reinterpret_cast<const bf16x8*>(vp_ + 64); \
;     ks0 = *reinterpret_cast<const bf16x8*>(kp_); ks1 = *reinterpret_cast<const bf16x8*>(kp_ + 64); ks2 = *reinterpret_cast<const bf16x8*>(kp_ + 128); } while (0)
; #define SWAIT() asm volatile("s_waitcnt vmcnt(0)" ::: "memory")
; __device__ __forceinline__ void attn_unit2(const bf16_t* __restrict__ Qb, const bf16_t* __restrict__ Kh, const bf16_t* __restrict__ Vh, ...
;     ...
;   const int sr = tid >> 3, vc = (tid & 7) * 8, vst0 = v_st(sr, vc);
;   const int vgo0 = sr * LDV + vc;
;   const int kgo0 = sr * LDKK + vc, klo0 = sr * 384 + ((vc * 2) ^ (((sr >> 1) & 7) << 4));
;   int kb4[4];
; #pragma unroll
;   for (int q = 0; q < 4; ++q) kb4[q] = r32 * 384 + ((q * 32 + hi * 16) ^ (((r32 >> 1) & 7) << 4));
;   const int vb0 = (int)(uintptr_t)V_lds + v_rd_base(lane);
;   bf16x8 vs0, vs1, ks0, ks1, ks2;
;     ...
;   f32x16 p0, p1; float mn, al = 1.f; bf16x8 pa0, pa1, pa2, pa3; constexpr int NT = NCHUNK;
;   SLOAD(0); SWAIT(); SWRITE(0); BARRIER();
;     ...
;   if (wid < 4) {
.LBB0_458:
	s_cmp_lg_u32 0, -1
	s_cselect_b32 s0, 0, 0
	s_addk_i32 s0, 0x4000
	v_add_u32_e32 v173, s0, v213
	s_add_u32 s0, s40, s39
	s_addc_u32 s1, s41, 0
	v_lshl_add_u64 v[164:165], v[186:187], 1, s[0:1]
	s_lshl_b32 s0, s19, 3
	s_and_b32 s0, s0, 0xe00
	s_add_u32 s0, s22, s0
	v_mov_b32_e32 v14, v185
	v_mov_b32_e32 v15, v185
	s_addc_u32 s1, s23, 0
	v_mov_b32_e32 v0, v185
	v_mov_b32_e32 v1, v185
	v_mov_b32_e32 v2, v185
	v_mov_b32_e32 v3, v185
	v_mov_b32_e32 v4, v185
	v_mov_b32_e32 v5, v185
	v_mov_b32_e32 v6, v185
	v_mov_b32_e32 v7, v185
	v_mov_b32_e32 v8, v185
	v_mov_b32_e32 v9, v185
	v_mov_b32_e32 v10, v185
	v_mov_b32_e32 v11, v185
	v_mov_b32_e32 v12, v185
	v_mov_b32_e32 v13, v185
	v_mov_b64_e32 v[62:63], v[14:15]
	v_mov_b64_e32 v[46:47], v[14:15]
	v_mov_b64_e32 v[30:31], v[14:15]
	v_cmp_gt_u32_e64 s[6:7], 32, v204
	s_mov_b32 s42, 0
	v_add_u32_e32 v174, 0xe000, v210
	v_add_u32_e32 v175, 0xe000, v209
	v_add_u32_e32 v176, 0xe000, v208
	v_add_u32_e32 v177, 0xe000, v207
	v_lshl_add_u64 v[166:167], v[188:189], 1, s[0:1]
	v_mov_b32_e32 v178, 0xf149f2ca
	v_mov_b32_e32 v172, 0
	v_mov_b64_e32 v[60:61], v[12:13]
	v_mov_b64_e32 v[58:59], v[10:11]
	v_mov_b64_e32 v[56:57], v[8:9]
	v_mov_b64_e32 v[54:55], v[6:7]
	v_mov_b64_e32 v[52:53], v[4:5]
	v_mov_b64_e32 v[50:51], v[2:3]
	v_mov_b64_e32 v[48:49], v[0:1]
	v_mov_b64_e32 v[44:45], v[12:13]
	v_mov_b64_e32 v[42:43], v[10:11]
	v_mov_b64_e32 v[40:41], v[8:9]
	v_mov_b64_e32 v[38:39], v[6:7]
	v_mov_b64_e32 v[36:37], v[4:5]
	v_mov_b64_e32 v[34:35], v[2:3]
	v_mov_b64_e32 v[32:33], v[0:1]
	v_mov_b64_e32 v[28:29], v[12:13]
	v_mov_b64_e32 v[26:27], v[10:11]
	v_mov_b64_e32 v[24:25], v[8:9]
	v_mov_b64_e32 v[22:23], v[6:7]
	v_mov_b64_e32 v[20:21], v[4:5]
	v_mov_b64_e32 v[18:19], v[2:3]
	v_mov_b64_e32 v[16:17], v[0:1]
	s_mov_b32 s19, 0
	v_readlane_b32 s0, v247, 14
	v_readlane_b32 s1, v247, 15
	s_load_dwordx4 s[52:55], s[0:1], 0xc0
	s_waitcnt lgkmcnt(0)
	s_add_u32 s64, s52, s28
	s_addc_u32 s65, s53, 0
	s_add_u32 s66, s52, 0x1b330000
	s_addc_u32 s67, s53, 0
	s_add_u32 s68, s52, 0x28780000
	s_addc_u32 s69, s53, 0
	s_add_u32 s70, s52, 0x1b360000
	s_addc_u32 s71, s53, 0

; #define SLOAD(t) do { const long r0_ = TROW(t); const bf16_t* vp_ = Vh + r0_ * LDV + vgo0; const bf16_t* kp_ = Kh + r0_ * LDKK + kgo0; \
;     vs0 = *reinterpret_cast<const bf16x8*>(vp_); vs1 = *reinterpret_cast<const bf16x8*>(vp_ + 64); \
;     ks0 = *reinterpret_cast<const bf16x8*>(kp_); ks1 = *reinterpret_cast<const bf16x8*>(kp_ + 64); ks2 = *reinterpret_cast<const bf16x8*>(kp_ + 128); } while (0)
; __device__ __forceinline__ void partialSM(f32x16& p0, f32x16& p1, float& m_reg, float& mn, float& alpha) {
;   constexpr float C = SCALE * 1.4426950408889634f;
;   float pmax = p0[0];
; #pragma unroll
;   for (int r = 1; r < 16; ++r) pmax = fmaxf(pmax, p0[r]);
; #pragma unroll
;   for (int r = 0; r < 16; ++r) pmax = fmaxf(pmax, p1[r]);
;   { auto rr = __builtin_amdgcn_permlane32_swap(__float_as_uint(pmax), __float_as_uint(pmax), false, false);
;     pmax = fmaxf(__uint_as_float(rr[0]), __uint_as_float(rr[1])); }
;   if (__builtin_expect(__all(pmax - m_reg <= THR / SCALE), 1)) { mn = m_reg; alpha = 1.f; }
;   else { mn = fmaxf(m_reg, pmax); alpha = __builtin_amdgcn_exp2f((m_reg - mn) * C); m_reg = mn; }
;   float mnC = -mn * C;
; #pragma unroll
;   for (int r = 0; r < 16; ++r) p0[r] = fmaf(p0[r], C, mnC);
; #pragma unroll
;   for (int r = 0; r < 16; ++r) p1[r] = fmaf(p1[r], C, mnC);
; #pragma unroll
;   for (int r = 0; r < 16; ++r) p0[r] = __builtin_amdgcn_exp2f(p0[r]);
; }
; __device__ __forceinline__ void finishSM(f32x16& p0, f32x16& p1, float alpha, float& l_reg, bf16x8& pa0, bf16x8& pa1, bf16x8& pa2, bf16x8& pa3) {
; #pragma unroll
;   for (int r = 0; r < 16; ++r) p1[r] = __builtin_amdgcn_exp2f(p1[r]);
;   float ps = 0;
; #pragma unroll
;   for (int r = 0; r < 16; ++r) ps += p0[r];
; #pragma unroll
;   for (int r = 0; r < 16; ++r) ps += p1[r];
;   { auto rr = __builtin_amdgcn_permlane32_swap(__float_as_uint(ps), __float_as_uint(ps), false, false);
;     ps = __uint_as_float(rr[0]) + __uint_as_float(rr[1]); }
;   l_reg = l_reg * alpha + ps;
;     ...
;   PK4(p0, 0, pa0); PK4(p0, 8, pa1); PK4(p1, 0, pa2); PK4(p1, 8, pa3);
; __device__ __forceinline__ void attn_unit2(const bf16_t* __restrict__ Qb, const bf16_t* __restrict__ Kh, const bf16_t* __restrict__ Vh, ...
;     ...
;   f32x16 p0, p1; float mn, al = 1.f; bf16x8 pa0, pa1, pa2, pa3; constexpr int NT = NCHUNK;
;   SLOAD(0); SWAIT(); SWRITE(0); BARRIER();
;     ...
;   if (wid < 4) {
.Lback0_a:
	v_max3_f32 v248, v64, v65, v66
	v_max3_f32 v249, v80, v81, v82
	v_max3_f32 v248, v248, v67, v68
	v_max3_f32 v249, v249, v83, v84
	v_max3_f32 v248, v248, v69, v70
	v_max3_f32 v249, v249, v85, v86
	v_max3_f32 v248, v248, v71, v72
	v_max3_f32 v249, v249, v87, v88
	v_max3_f32 v248, v248, v73, v74
	v_max3_f32 v249, v249, v89, v90
	v_max3_f32 v248, v248, v75, v76
	v_max3_f32 v249, v249, v91, v92
	v_max3_f32 v248, v248, v77, v78
	v_max3_f32 v249, v249, v93, v94
	v_max3_f32 v248, v248, v79, v95
	v_max_f32_e32 v248, v248, v249
	v_mov_b32_e32 v249, v248
	s_nop 1
	v_permlane32_swap_b32_e32 v248, v249
	v_max_f32_e32 v248, v248, v249
	v_sub_f32_e32 v249, v248, v178
	v_cmp_ge_f32_e32 vcc, s30, v249
	s_cmp_eq_u64 vcc, exec
	s_cselect_b64 s[8:9], -1, 0
	s_waitcnt lgkmcnt(0)
	s_barrier
	s_waitcnt vmcnt(0)
	ds_write_b128 v212, v[144:147] offset:16384
	ds_write_b128 v212, v[148:151] offset:17408
	ds_write_b128 v211, v[152:155] offset:57344
	ds_write_b128 v211, v[156:159] offset:57472
	ds_write_b128 v211, v[160:163] offset:57600
	v_lshl_add_u64 v[148:149], s[64:65], 0, v[166:167]
	v_lshl_add_u64 v[160:161], s[66:67], 0, v[164:165]
	global_load_dwordx4 v[144:147], v[148:149], off offset:256
	s_nop 0
	global_load_dwordx4 v[148:151], v[148:149], off offset:384
	global_load_dwordx4 v[152:155], v[160:161], off
	global_load_dwordx4 v[156:159], v[160:161], off offset:128
	s_nop 0
	global_load_dwordx4 v[160:163], v[160:161], off offset:256
	v_mov_b32_e32 v180, v76
	v_mov_b32_e32 v181, v77
	v_mov_b32_e32 v76, v90
	v_mov_b32_e32 v77, v91
	v_mov_b32_e32 v186, v72
	v_mov_b32_e32 v187, v73
	v_mov_b32_e32 v182, v74
	v_mov_b32_e32 v183, v75
	v_mov_b32_e32 v74, v92
	v_mov_b32_e32 v75, v93
	v_mov_b32_e32 v73, v94
	v_mov_b32_e32 v72, v95
	s_cbranch_scc0 .Lslow_a0
	v_mov_b32_e32 v179, 1.0
.Lafter_a0:
	v_mul_f32_e32 v90, 0xbdd53b94, v178
	v_fmamk_f32 v64, v64, 0x3dd53b94, v90
	v_fmamk_f32 v65, v65, 0x3dd53b94, v90
	v_exp_f32_e32 v64, v64
	v_fmamk_f32 v66, v66, 0x3dd53b94, v90
	v_exp_f32_e32 v65, v65
	v_fmamk_f32 v67, v67, 0x3dd53b94, v90
	v_exp_f32_e32 v66, v66
	v_fmamk_f32 v68, v68, 0x3dd53b94, v90
	v_fmamk_f32 v73, v73, 0x3dd53b94, v90
	v_exp_f32_e32 v67, v67
	v_fmamk_f32 v69, v69, 0x3dd53b94, v90
	v_fmamk_f32 v92, v187, 0x3dd53b94, v90
	v_exp_f32_e32 v68, v68
	v_exp_f32_e32 v187, v73
	v_add_f32_e32 v73, 0, v64
	v_fmamk_f32 v70, v70, 0x3dd53b94, v90
	v_exp_f32_e32 v69, v69
	v_add_f32_e32 v73, v65, v73
	v_fmamk_f32 v71, v71, 0x3dd53b94, v90
	v_exp_f32_e32 v70, v70
	v_add_f32_e32 v73, v66, v73
	v_fmamk_f32 v91, v186, 0x3dd53b94, v90
	v_exp_f32_e32 v71, v71
	v_add_f32_e32 v73, v67, v73
	v_fmamk_f32 v93, v182, 0x3dd53b94, v90
	v_fmamk_f32 v94, v183, 0x3dd53b94, v90
	v_fmamk_f32 v95, v180, 0x3dd53b94, v90
	v_fmamk_f32 v180, v181, 0x3dd53b94, v90
	v_fmamk_f32 v78, v78, 0x3dd53b94, v90
	v_fmamk_f32 v79, v79, 0x3dd53b94, v90
	v_fmamk_f32 v80, v80, 0x3dd53b94, v90
	v_fmamk_f32 v81, v81, 0x3dd53b94, v90
	v_fmamk_f32 v82, v82, 0x3dd53b94, v90
	v_fmamk_f32 v83, v83, 0x3dd53b94, v90
	v_fmamk_f32 v84, v84, 0x3dd53b94, v90
	v_fmamk_f32 v85, v85, 0x3dd53b94, v90
	v_fmamk_f32 v86, v86, 0x3dd53b94, v90
	v_fmamk_f32 v87, v87, 0x3dd53b94, v90
	v_fmamk_f32 v88, v88, 0x3dd53b94, v90
	v_fmamk_f32 v89, v89, 0x3dd53b94, v90
	v_fmamk_f32 v76, v76, 0x3dd53b94, v90
	v_fmamk_f32 v77, v77, 0x3dd53b94, v90
	v_fmamk_f32 v74, v74, 0x3dd53b94, v90
	v_fmamk_f32 v75, v75, 0x3dd53b94, v90
	v_fmac_f32_e32 v90, 0x3dd53b94, v72
	v_exp_f32_e32 v72, v91
	v_add_f32_e32 v73, v68, v73
	v_exp_f32_e32 v91, v92
	v_add_f32_e32 v73, v69, v73
	v_exp_f32_e32 v92, v93
	v_add_f32_e32 v73, v70, v73
	v_exp_f32_e32 v93, v94
	v_add_f32_e32 v73, v71, v73
	v_exp_f32_e32 v94, v95
	v_add_f32_e32 v73, v72, v73
	v_exp_f32_e32 v95, v180
	v_add_f32_e32 v73, v91, v73
	v_exp_f32_e32 v78, v78
	v_add_f32_e32 v73, v92, v73
	v_exp_f32_e32 v79, v79
	v_add_f32_e32 v73, v93, v73
	v_exp_f32_e32 v80, v80
	v_add_f32_e32 v73, v94, v73
	v_exp_f32_e32 v81, v81
	v_add_f32_e32 v73, v95, v73
	v_exp_f32_e32 v82, v82
	v_add_f32_e32 v73, v78, v73
	v_exp_f32_e32 v83, v83
	v_add_f32_e32 v73, v79, v73
	v_exp_f32_e32 v84, v84
	v_add_f32_e32 v73, v80, v73
	v_exp_f32_e32 v85, v85
	v_add_f32_e32 v73, v81, v73
	v_exp_f32_e32 v86, v86
	v_add_f32_e32 v73, v82, v73
	v_exp_f32_e32 v87, v87
	v_add_f32_e32 v73, v83, v73
	v_exp_f32_e32 v88, v88
	v_add_f32_e32 v73, v84, v73
	v_exp_f32_e32 v89, v89
	v_add_f32_e32 v73, v85, v73
	v_exp_f32_e32 v182, v76
	v_add_f32_e32 v73, v86, v73
	v_exp_f32_e32 v77, v77
	v_add_f32_e32 v73, v87, v73
	v_exp_f32_e32 v183, v74
	v_add_f32_e32 v73, v88, v73
	v_exp_f32_e32 v186, v75
	v_add_f32_e32 v73, v89, v73
	v_add_f32_e32 v73, v182, v73
	v_exp_f32_e32 v90, v90
	v_add_f32_e32 v73, v77, v73
	v_add_f32_e32 v73, v183, v73
	v_add_f32_e32 v73, v186, v73
	v_add_f32_e32 v73, v187, v73
	v_add_f32_e32 v180, v90, v73
	v_mov_b32_e32 v181, v180
	v_cvt_pk_bf16_f32 v64, v64, v65
	v_cvt_pk_bf16_f32 v65, v66, v67
	v_cvt_pk_bf16_f32 v66, v68, v69
	v_cvt_pk_bf16_f32 v67, v70, v71
	v_cvt_pk_bf16_f32 v68, v72, v91
	v_cvt_pk_bf16_f32 v69, v92, v93
	v_cvt_pk_bf16_f32 v70, v94, v95
	v_cvt_pk_bf16_f32 v71, v78, v79
	v_cvt_pk_bf16_f32 v72, v80, v81
	v_cvt_pk_bf16_f32 v73, v82, v83
	v_cvt_pk_bf16_f32 v74, v84, v85
	v_cvt_pk_bf16_f32 v75, v86, v87
	v_cvt_pk_bf16_f32 v76, v88, v89
	v_cvt_pk_bf16_f32 v77, v182, v77
	v_cvt_pk_bf16_f32 v78, v183, v186
	v_cvt_pk_bf16_f32 v79, v187, v90
	s_nop 1
	v_permlane32_swap_b32_e32 v180, v181
	v_permlane32_swap_b32_e32 v64, v66
	v_permlane32_swap_b32_e32 v65, v67
	v_permlane32_swap_b32_e32 v68, v70
	v_permlane32_swap_b32_e32 v69, v71
	v_permlane32_swap_b32_e32 v72, v74
	v_permlane32_swap_b32_e32 v73, v75
	v_permlane32_swap_b32_e32 v76, v78
	v_permlane32_swap_b32_e32 v77, v79
	ds_read_b64_tr_b16 v[80:81], v206 offset:0
	ds_read_b64_tr_b16 v[82:83], v206 offset:0x800
	ds_read_b64_tr_b16 v[84:85], v206 offset:0x1000
	ds_read_b64_tr_b16 v[86:87], v206 offset:0x1800
	ds_read_b64_tr_b16 v[88:89], v206 offset:0x2000
	ds_read_b64_tr_b16 v[90:91], v206 offset:0x2800
	ds_read_b64_tr_b16 v[92:93], v206 offset:0x3000
	ds_read_b64_tr_b16 v[94:95], v206 offset:0x3800
	ds_read_b64_tr_b16 v[186:187], v206 offset:0x200
	ds_read_b64_tr_b16 v[188:189], v206 offset:0xa00
	ds_read_b64_tr_b16 v[190:191], v206 offset:0x1200
	ds_read_b64_tr_b16 v[192:193], v206 offset:0x1a00
	ds_read_b64_tr_b16 v[194:195], v206 offset:0x2200
	ds_read_b64_tr_b16 v[196:197], v206 offset:0x2a00
	ds_read_b64_tr_b16 v[214:215], v206 offset:0x3200
	ds_read_b64_tr_b16 v[216:217], v206 offset:0x3a00
	s_waitcnt lgkmcnt(8)
; #define SBAR() __builtin_amdgcn_sched_barrier(0)
; __device__ __forceinline__ void qkt2(f32x16& p0, f32x16& p1, const char* Ks, const bf16x8* qr, const int* kb4) {
;     ...
;   p0 = f32x16{}; p1 = f32x16{};
;   bf16x8 a0 = KLD(0, 0), b0 = KLD(0, 1), a1 = KLD(1, 0), b1 = KLD(1, 1), a2, b2;
;     ...
;   QSTEP(0, a0, b0, a2, b2); QSTEP(1, a1, b1, a0, b0); QSTEP(2, a2, b2, a1, b1);
;   QSTEP(3, a0, b0, a2, b2); QSTEP(4, a1, b1, a0, b0); QSTEP(5, a2, b2, a1, b1);
;   QSTEP(6, a0, b0, a2, b2); QSTEP(7, a1, b1, a0, b0); QSTEP(8, a2, b2, a1, b1);
;   QSTEP(9, a0, b0, a2, b2); QSTEP(10, a1, b1, a0, b0); QSTEP(11, a2, b2, a1, b1);
;     ...
; }
; template <int D0> __device__ __forceinline__ void v_issue(VSet& s, int vb) {
;   s.l0 = tr_read<v_rd_off(D0, 0, 0)>(vb); s.h0 = tr_read<v_rd_off(D0, 0, 1)>(vb); s.l1 = tr_read<v_rd_off(D0, 1, 0)>(vb); s.h1 = tr_read<v_rd_off(D0, 1, 1)>(vb);
;   s.l2 = tr_read<v_rd_off(D0, 2, 0)>(vb); s.h2 = tr_read<v_rd_off(D0, 2, 1)>(vb); s.l3 = tr_read<v_rd_off(D0, 3, 0)>(vb); s.h3 = tr_read<v_rd_off(D0, 3, 1)>(vb);
; }
; __device__ __forceinline__ void v_mma(f32x16& od, VSet& s, bf16x8 pa0, bf16x8 pa1, bf16x8 pa2, bf16x8 pa3) {
;   asm volatile("" : "+v"(s.l0), "+v"(s.h0), "+v"(s.l1), "+v"(s.h1), "+v"(s.l2), "+v"(s.h2), "+v"(s.l3), "+v"(s.h3));
;     ...
;   od = __builtin_amdgcn_mfma_f32_32x32x16_bf16(pa0, PK(s.l0, s.h0), od, 0, 0, 0);
;   od = __builtin_amdgcn_mfma_f32_32x32x16_bf16(pa1, PK(s.l1, s.h1), od, 0, 0, 0);
;   od = __builtin_amdgcn_mfma_f32_32x32x16_bf16(pa2, PK(s.l2, s.h2), od, 0, 0, 0);
;   od = __builtin_amdgcn_mfma_f32_32x32x16_bf16(pa3, PK(s.l3, s.h3), od, 0, 0, 0);
;     ...
; }
; __device__ __forceinline__ void pv2(f32x16* o, int vb, bf16x8 pa0, bf16x8 pa1, bf16x8 pa2, bf16x8 pa3) {
;   VSet X, Y;
;   SBAR(); v_issue<0>(X, vb); v_issue<1>(Y, vb);
;   asm volatile("s_waitcnt lgkmcnt(8)" ::: "memory"); SBAR(); v_mma(o[0], X, pa0, pa1, pa2, pa3); SBAR();
;   v_issue<2>(X, vb);
;   asm volatile("s_waitcnt lgkmcnt(8)" ::: "memory"); SBAR(); v_mma(o[1], Y, pa0, pa1, pa2, pa3); SBAR();
;   v_issue<3>(Y, vb);
;   asm volatile("s_waitcnt lgkmcnt(8)" ::: "memory"); SBAR(); v_mma(o[2], X, pa0, pa1, pa2, pa3); SBAR();
;   asm volatile("s_waitcnt lgkmcnt(0)" ::: "memory"); SBAR(); v_mma(o[3], Y, pa0, pa1, pa2, pa3); SBAR();
; }
	s_nop 0
	s_nop 0
	v_mfma_f32_32x32x16_bf16 v[0:15], v[64:67], v[80:83], v[0:15]
	v_mfma_f32_32x32x16_bf16 v[0:15], v[68:71], v[84:87], v[0:15]
	v_mfma_f32_32x32x16_bf16 v[0:15], v[72:75], v[88:91], v[0:15]
	v_mfma_f32_32x32x16_bf16 v[0:15], v[76:79], v[92:95], v[0:15]
	ds_read_b64_tr_b16 v[80:81], v206 offset:0x400
	ds_read_b64_tr_b16 v[82:83], v206 offset:0xc00
	ds_read_b64_tr_b16 v[84:85], v206 offset:0x1400
	ds_read_b64_tr_b16 v[86:87], v206 offset:0x1c00
	ds_read_b64_tr_b16 v[88:89], v206 offset:0x2400
	ds_read_b64_tr_b16 v[90:91], v206 offset:0x2c00
	ds_read_b64_tr_b16 v[92:93], v206 offset:0x3400
	ds_read_b64_tr_b16 v[94:95], v206 offset:0x3c00
	s_waitcnt lgkmcnt(8)
	s_nop 0
	v_mfma_f32_32x32x16_bf16 v[48:63], v[64:67], v[186:189], v[48:63]
	v_mfma_f32_32x32x16_bf16 v[48:63], v[68:71], v[190:193], v[48:63]
	v_mfma_f32_32x32x16_bf16 v[48:63], v[72:75], v[194:197], v[48:63]
	v_mfma_f32_32x32x16_bf16 v[48:63], v[76:79], v[214:217], v[48:63]
	ds_read_b64_tr_b16 v[186:187], v206 offset:0x600
	ds_read_b64_tr_b16 v[188:189], v206 offset:0xe00
	ds_read_b64_tr_b16 v[190:191], v206 offset:0x1600
	ds_read_b64_tr_b16 v[192:193], v206 offset:0x1e00
	ds_read_b64_tr_b16 v[194:195], v206 offset:0x2600
	ds_read_b64_tr_b16 v[196:197], v206 offset:0x2e00
	ds_read_b64_tr_b16 v[214:215], v206 offset:0x3600
	ds_read_b64_tr_b16 v[216:217], v206 offset:0x3e00
	s_waitcnt lgkmcnt(8)
	s_nop 0
	v_mfma_f32_32x32x16_bf16 v[32:47], v[64:67], v[80:83], v[32:47]
	v_mfma_f32_32x32x16_bf16 v[32:47], v[68:71], v[84:87], v[32:47]
	v_mfma_f32_32x32x16_bf16 v[32:47], v[72:75], v[88:91], v[32:47]
	v_mfma_f32_32x32x16_bf16 v[32:47], v[76:79], v[92:95], v[32:47]
	s_waitcnt lgkmcnt(0)
	s_nop 0
	v_mfma_f32_32x32x16_bf16 v[16:31], v[64:67], v[186:189], v[16:31]
	v_mfma_f32_32x32x16_bf16 v[16:31], v[68:71], v[190:193], v[16:31]
	v_mfma_f32_32x32x16_bf16 v[16:31], v[72:75], v[194:197], v[16:31]
	v_mfma_f32_32x32x16_bf16 v[16:31], v[76:79], v[214:217], v[16:31]
	s_waitcnt lgkmcnt(0)
	s_barrier
	ds_read_b128 v[64:67], v174 offset:12288
	ds_read_b128 v[186:189], v175 offset:12288
	ds_read_b128 v[190:193], v209 offset:57344
	ds_read_b128 v[194:197], v208 offset:57344
	ds_read_b128 v[68:71], v210 offset:57344
	ds_read_b128 v[214:217], v176 offset:12288
	s_waitcnt lgkmcnt(1)
	v_mfma_f32_32x32x16_bf16 v[80:95], v[68:71], v[96:99], 0
	v_mfma_f32_32x32x16_bf16 v[64:79], v[64:67], v[96:99], 0
	ds_read_b128 v[218:221], v207 offset:57344
	ds_read_b128 v[222:225], v177 offset:12288
	v_mfma_f32_32x32x16_bf16 v[80:95], v[190:193], v[100:103], v[80:95]
	v_mfma_f32_32x32x16_bf16 v[64:79], v[186:189], v[100:103], v[64:79]
	ds_read_b128 v[186:189], v210 offset:57472
	ds_read_b128 v[190:193], v174 offset:12416
	v_mfma_f32_32x32x16_bf16 v[80:95], v[194:197], v[104:107], v[80:95]
	s_waitcnt lgkmcnt(4)
	v_mfma_f32_32x32x16_bf16 v[64:79], v[214:217], v[104:107], v[64:79]
	ds_read_b128 v[194:197], v209 offset:57472
	ds_read_b128 v[214:217], v175 offset:12416
	s_waitcnt lgkmcnt(4)
	v_mfma_f32_32x32x16_bf16 v[80:95], v[218:221], v[108:111], v[80:95]
	v_mfma_f32_32x32x16_bf16 v[64:79], v[222:225], v[108:111], v[64:79]
	ds_read_b128 v[218:221], v208 offset:57472
	ds_read_b128 v[222:225], v176 offset:12416
	s_waitcnt lgkmcnt(4)
	v_mfma_f32_32x32x16_bf16 v[80:95], v[186:189], v[112:115], v[80:95]
	v_mfma_f32_32x32x16_bf16 v[64:79], v[190:193], v[112:115], v[64:79]
	ds_read_b128 v[186:189], v207 offset:57472
	ds_read_b128 v[190:193], v177 offset:12416
	s_waitcnt lgkmcnt(4)
	v_mfma_f32_32x32x16_bf16 v[80:95], v[194:197], v[116:119], v[80:95]
	v_mfma_f32_32x32x16_bf16 v[64:79], v[214:217], v[116:119], v[64:79]
	ds_read_b128 v[194:197], v210 offset:57600
	ds_read_b128 v[214:217], v174 offset:12544
	s_waitcnt lgkmcnt(4)
	v_mfma_f32_32x32x16_bf16 v[80:95], v[218:221], v[120:123], v[80:95]
	v_mfma_f32_32x32x16_bf16 v[64:79], v[222:225], v[120:123], v[64:79]
	ds_read_b128 v[218:221], v209 offset:57600
	ds_read_b128 v[222:225], v175 offset:12544
	s_waitcnt lgkmcnt(4)
	v_mfma_f32_32x32x16_bf16 v[80:95], v[186:189], v[124:127], v[80:95]
	v_mfma_f32_32x32x16_bf16 v[64:79], v[190:193], v[124:127], v[64:79]
	ds_read_b128 v[186:189], v208 offset:57600
	ds_read_b128 v[190:193], v176 offset:12544
	s_waitcnt lgkmcnt(4)
	v_mfma_f32_32x32x16_bf16 v[80:95], v[194:197], v[132:135], v[80:95]
	v_mfma_f32_32x32x16_bf16 v[64:79], v[214:217], v[132:135], v[64:79]
	ds_read_b128 v[194:197], v207 offset:57600
	ds_read_b128 v[214:217], v177 offset:12544
	s_waitcnt lgkmcnt(4)
	v_mfma_f32_32x32x16_bf16 v[80:95], v[218:221], v[140:143], v[80:95]
	v_mfma_f32_32x32x16_bf16 v[64:79], v[222:225], v[140:143], v[64:79]
	s_waitcnt lgkmcnt(2)
	v_mfma_f32_32x32x16_bf16 v[80:95], v[186:189], v[128:131], v[80:95]
	v_mfma_f32_32x32x16_bf16 v[64:79], v[190:193], v[128:131], v[64:79]
	s_waitcnt lgkmcnt(0)
	v_mfma_f32_32x32x16_bf16 v[80:95], v[194:197], v[136:139], v[80:95]
	v_mfma_f32_32x32x16_bf16 v[64:79], v[214:217], v[136:139], v[64:79]
	s_nop 9
	v_max_f32_e32 v182, v81, v81
	v_max_f32_e32 v183, v80, v80
	v_max_f32_e32 v182, v183, v182
	v_max3_f32 v182, v182, v82, v83
	v_max3_f32 v182, v182, v84, v85
	v_max3_f32 v182, v182, v86, v87
	v_max3_f32 v182, v182, v88, v89
	v_max3_f32 v182, v182, v90, v91
	v_max3_f32 v182, v182, v92, v93
	v_max3_f32 v182, v182, v94, v95
	v_max3_f32 v182, v182, v64, v65
	v_max3_f32 v182, v182, v66, v67
	v_max3_f32 v182, v182, v68, v69
	v_max3_f32 v182, v182, v70, v71
	v_max3_f32 v182, v182, v72, v73
	v_max3_f32 v182, v182, v74, v75
	v_max3_f32 v182, v182, v76, v77
	v_max3_f32 v182, v182, v78, v79
	v_mov_b32_e32 v183, v182
	s_nop 1
	v_permlane32_swap_b32_e32 v182, v183
	v_max_f32_e32 v183, v183, v183
	v_max_f32_e32 v182, v182, v182
	s_waitcnt lgkmcnt(0)
	s_barrier
	v_max_f32_e32 v182, v182, v183
	s_waitcnt vmcnt(0)
	v_sub_f32_e32 v183, v182, v178
	v_cmp_ge_f32_e64 s[8:9], s30, v183
	s_cmpk_gt_u32 s19, 0xfd
	ds_write_b128 v212, v[144:147]
	ds_write_b128 v212, v[148:151] offset:1024
	ds_write_b128 v211, v[152:155] offset:32768
	ds_write_b128 v211, v[156:159] offset:32896
	ds_write_b128 v211, v[160:163] offset:33024
	s_cbranch_scc1 .LBB0_465
	v_lshl_add_u64 v[148:149], s[68:69], 0, v[166:167]
	v_lshl_add_u64 v[160:161], s[70:71], 0, v[164:165]
	global_load_dwordx4 v[144:147], v[148:149], off offset:256
	s_nop 0
	global_load_dwordx4 v[148:151], v[148:149], off offset:384
	global_load_dwordx4 v[152:155], v[160:161], off
	global_load_dwordx4 v[156:159], v[160:161], off offset:128
	s_nop 0
	global_load_dwordx4 v[160:163], v[160:161], off offset:256
